# final RMS norm pipelined with uniform counted waits (vmcnt 8), KV-cache copy x2; stacked on first_rows/sb_gemv/ssd-prep/lru fixes
# baseline (speedup 1.0000x reference)
.LBB0_1585:
	s_mov_b32 s2, 37
	v_readlane_b32 s3, v254, 4
	v_ashrrev_i32_e32 v0, 6, v179
	s_nop 0
	v_add_u32_e32 v16, s3, v0
	s_movk_i32 s3, 0x4000
	v_cmp_gt_i32_e32 vcc, s3, v16
	s_and_saveexec_b64 s[4:5], vcc
	v_readlane_b32 s8, v254, 55
	v_readlane_b32 s6, v254, 53
	v_readlane_b32 s9, v254, 56
	v_readlane_b32 s7, v254, 54
	s_cbranch_execz .LBB0_1588
	s_ashr_i32 s3, s2, 31
	s_lshl_b64 s[2:3], s[2:3], 3
	s_add_u32 s0, s0, s2
	s_addc_u32 s1, s1, s3
	s_load_dwordx2 s[0:1], s[0:1], 0x0
	v_lshlrev_b32_e32 v0, 4, v179
	v_and_b32_e32 v17, 0x3f0, v0
	s_mov_b64 s[2:3], 0
	s_mov_b32 s4, 0x800000
	s_waitcnt lgkmcnt(0)
	global_load_dwordx4 v[0:3], v17, s[0:1]
	global_load_dwordx4 v[4:7], v17, s[0:1] offset:1024
	global_load_dwordx4 v[8:11], v17, s[0:1] offset:2048
	global_load_dwordx4 v[12:15], v17, s[0:1] offset:3072
	v_ashrrev_i32_e32 v17, 31, v16
	v_lshlrev_b64 v[18:19], 12, v[16:17]
	v_and_b32_e32 v17, 63, v179
	v_lshl_or_b32 v18, v17, 4, v18
	v_lshl_add_u64 v[18:19], s[30:31], 0, v[18:19]
	s_mov_b64 s[0:1], 0xc00
	v_lshl_add_u64 v[18:19], v[18:19], 0, s[0:1]
	v_mov_b32_e32 v17, 0x358637bd
	s_movk_i32 s5, 0x3fff
	global_load_dwordx4 v[20:23], v[18:19], off offset:-3072
	global_load_dwordx4 v[24:27], v[18:19], off offset:-2048
	global_load_dwordx4 v[28:31], v[18:19], off offset:-1024
	global_load_dwordx4 v[32:35], v[18:19], off
	s_waitcnt vmcnt(0)
.LBB0_1587:
	v_lshl_add_u64 v[60:61], v[18:19], 0, s[8:9]
	global_load_dwordx4 v[44:47], v[60:61], off offset:-3072
	global_load_dwordx4 v[48:51], v[60:61], off offset:-2048
	global_load_dwordx4 v[52:55], v[60:61], off offset:-1024
	global_load_dwordx4 v[56:59], v[60:61], off
	v_add_u32_e32 v16, s6, v16
	s_waitcnt vmcnt(8)
	v_mul_f32_e32 v36, v21, v21
	v_mul_f32_e32 v37, v23, v23
	v_mul_f32_e32 v38, v25, v25
	v_mul_f32_e32 v39, v27, v27
	v_mul_f32_e32 v40, v29, v29
	v_mul_f32_e32 v41, v31, v31
	v_fmac_f32_e32 v36, v20, v20
	v_fmac_f32_e32 v37, v22, v22
	v_fmac_f32_e32 v38, v24, v24
	v_fmac_f32_e32 v39, v26, v26
	v_mul_f32_e32 v42, v33, v33
	v_mul_f32_e32 v43, v35, v35
	v_fmac_f32_e32 v40, v28, v28
	v_fmac_f32_e32 v41, v30, v30
	v_add_f32_e32 v36, v36, v37
	v_add_f32_e32 v37, v38, v39
	v_fmac_f32_e32 v42, v32, v32
	v_fmac_f32_e32 v43, v34, v34
	v_add_f32_e32 v38, v40, v41
	v_add_f32_e32 v36, v36, v37
	v_add_f32_e32 v39, v42, v43
	v_add_f32_e32 v36, v36, v38
	v_add_f32_e32 v36, v36, v39
	s_nop 1
	v_add_f32_dpp v36, v36, v36 quad_perm:[1,0,3,2] row_mask:0xf bank_mask:0xf bound_ctrl:1
	s_nop 1
	v_add_f32_dpp v36, v36, v36 quad_perm:[2,3,0,1] row_mask:0xf bank_mask:0xf bound_ctrl:1
	s_nop 1
	v_add_f32_dpp v36, v36, v36 row_half_mirror row_mask:0xf bank_mask:0xf bound_ctrl:1
	s_nop 1
	v_add_f32_dpp v36, v36, v36 row_mirror row_mask:0xf bank_mask:0xf bound_ctrl:1
	v_mov_b32_e32 v37, v36
	s_nop 1
	v_permlane16_swap_b32_e32 v36, v37
	v_add_f32_e32 v36, v36, v37
	v_mov_b32_e32 v37, v36
	s_nop 1
	v_permlane32_swap_b32_e32 v36, v37
	v_add_f32_e32 v36, v36, v37
	v_fmamk_f32 v36, v36, 0x3a800000, v17
	v_mul_f32_e32 v37, 0x4b800000, v36
	v_cmp_gt_f32_e32 vcc, s4, v36
	s_nop 1
	v_cndmask_b32_e32 v36, v36, v37, vcc
	v_rsq_f32_e32 v36, v36
	s_nop 0
	v_mul_f32_e32 v37, 0x45800000, v36
	v_cndmask_b32_e32 v36, v36, v37, vcc
	v_pk_mul_f32 v[20:21], v[20:21], v[36:37] op_sel_hi:[1,0]
	v_pk_mul_f32 v[22:23], v[22:23], v[36:37] op_sel_hi:[1,0]
	v_pk_mul_f32 v[24:25], v[24:25], v[36:37] op_sel_hi:[1,0]
	v_pk_mul_f32 v[26:27], v[26:27], v[36:37] op_sel_hi:[1,0]
	v_pk_mul_f32 v[28:29], v[28:29], v[36:37] op_sel_hi:[1,0]
	v_pk_mul_f32 v[30:31], v[30:31], v[36:37] op_sel_hi:[1,0]
	v_pk_mul_f32 v[32:33], v[32:33], v[36:37] op_sel_hi:[1,0]
	v_pk_mul_f32 v[34:35], v[34:35], v[36:37] op_sel_hi:[1,0]
	v_pk_mul_f32 v[22:23], v[2:3], v[22:23]
	v_pk_mul_f32 v[20:21], v[0:1], v[20:21]
	v_pk_mul_f32 v[26:27], v[6:7], v[26:27]
	v_pk_mul_f32 v[24:25], v[4:5], v[24:25]
	v_pk_mul_f32 v[30:31], v[10:11], v[30:31]
	v_pk_mul_f32 v[28:29], v[8:9], v[28:29]
	v_pk_mul_f32 v[34:35], v[14:15], v[34:35]
	v_pk_mul_f32 v[32:33], v[12:13], v[32:33]
	global_store_dwordx4 v[18:19], v[20:23], off offset:-3072
	global_store_dwordx4 v[18:19], v[24:27], off offset:-2048
	global_store_dwordx4 v[18:19], v[28:31], off offset:-1024
	global_store_dwordx4 v[18:19], v[32:35], off
	v_lshl_add_u64 v[18:19], v[60:61], 0, s[8:9]
	global_load_dwordx4 v[20:23], v[18:19], off offset:-3072
	global_load_dwordx4 v[24:27], v[18:19], off offset:-2048
	global_load_dwordx4 v[28:31], v[18:19], off offset:-1024
	global_load_dwordx4 v[32:35], v[18:19], off
	v_add_u32_e32 v16, s6, v16
	v_cmp_lt_i32_e64 s[0:1], s5, v16
	s_or_b64 s[2:3], s[0:1], s[2:3]
	s_waitcnt vmcnt(8)
	v_mul_f32_e32 v36, v45, v45
	v_mul_f32_e32 v37, v47, v47
	v_mul_f32_e32 v38, v49, v49
	v_mul_f32_e32 v39, v51, v51
	v_mul_f32_e32 v40, v53, v53
	v_mul_f32_e32 v41, v55, v55
	v_fmac_f32_e32 v36, v44, v44
	v_fmac_f32_e32 v37, v46, v46
	v_fmac_f32_e32 v38, v48, v48
	v_fmac_f32_e32 v39, v50, v50
	v_mul_f32_e32 v42, v57, v57
	v_mul_f32_e32 v43, v59, v59
	v_fmac_f32_e32 v40, v52, v52
	v_fmac_f32_e32 v41, v54, v54
	v_add_f32_e32 v36, v36, v37
	v_add_f32_e32 v37, v38, v39
	v_fmac_f32_e32 v42, v56, v56
	v_fmac_f32_e32 v43, v58, v58
	v_add_f32_e32 v38, v40, v41
	v_add_f32_e32 v36, v36, v37
	v_add_f32_e32 v39, v42, v43
	v_add_f32_e32 v36, v36, v38
	v_add_f32_e32 v36, v36, v39
	s_nop 1
	v_add_f32_dpp v36, v36, v36 quad_perm:[1,0,3,2] row_mask:0xf bank_mask:0xf bound_ctrl:1
	s_nop 1
	v_add_f32_dpp v36, v36, v36 quad_perm:[2,3,0,1] row_mask:0xf bank_mask:0xf bound_ctrl:1
	s_nop 1
	v_add_f32_dpp v36, v36, v36 row_half_mirror row_mask:0xf bank_mask:0xf bound_ctrl:1
	s_nop 1
	v_add_f32_dpp v36, v36, v36 row_mirror row_mask:0xf bank_mask:0xf bound_ctrl:1
	v_mov_b32_e32 v37, v36
	s_nop 1
	v_permlane16_swap_b32_e32 v36, v37
	v_add_f32_e32 v36, v36, v37
	v_mov_b32_e32 v37, v36
	s_nop 1
	v_permlane32_swap_b32_e32 v36, v37
	v_add_f32_e32 v36, v36, v37
	v_fmamk_f32 v36, v36, 0x3a800000, v17
	v_mul_f32_e32 v37, 0x4b800000, v36
	v_cmp_gt_f32_e32 vcc, s4, v36
	s_nop 1
	v_cndmask_b32_e32 v36, v36, v37, vcc
	v_rsq_f32_e32 v36, v36
	s_nop 0
	v_mul_f32_e32 v37, 0x45800000, v36
	v_cndmask_b32_e32 v36, v36, v37, vcc
	v_pk_mul_f32 v[44:45], v[44:45], v[36:37] op_sel_hi:[1,0]
	v_pk_mul_f32 v[46:47], v[46:47], v[36:37] op_sel_hi:[1,0]
	v_pk_mul_f32 v[48:49], v[48:49], v[36:37] op_sel_hi:[1,0]
	v_pk_mul_f32 v[50:51], v[50:51], v[36:37] op_sel_hi:[1,0]
	v_pk_mul_f32 v[52:53], v[52:53], v[36:37] op_sel_hi:[1,0]
	v_pk_mul_f32 v[54:55], v[54:55], v[36:37] op_sel_hi:[1,0]
	v_pk_mul_f32 v[56:57], v[56:57], v[36:37] op_sel_hi:[1,0]
	v_pk_mul_f32 v[58:59], v[58:59], v[36:37] op_sel_hi:[1,0]
	v_pk_mul_f32 v[46:47], v[2:3], v[46:47]
	v_pk_mul_f32 v[44:45], v[0:1], v[44:45]
	v_pk_mul_f32 v[50:51], v[6:7], v[50:51]
	v_pk_mul_f32 v[48:49], v[4:5], v[48:49]
	v_pk_mul_f32 v[54:55], v[10:11], v[54:55]
	v_pk_mul_f32 v[52:53], v[8:9], v[52:53]
	v_pk_mul_f32 v[58:59], v[14:15], v[58:59]
	v_pk_mul_f32 v[56:57], v[12:13], v[56:57]
	global_store_dwordx4 v[60:61], v[44:47], off offset:-3072
	global_store_dwordx4 v[60:61], v[48:51], off offset:-2048
	global_store_dwordx4 v[60:61], v[52:55], off offset:-1024
	global_store_dwordx4 v[60:61], v[56:59], off
	s_andn2_b64 exec, exec, s[2:3]
	s_cbranch_execnz .LBB0_1587
